# v66 + in-proj / ffn_in epilogues not re-aligned: leading wave group starts its epilogue while the other still multiplies; stagger kept through epilogue + peeled trip; one re-alignment barrier at the p
# baseline (speedup 1.0000x reference)
; #define PG8_WAIT_V(n) asm volatile("s_waitcnt vmcnt(" #n ")" ::: "memory")
; template <class Epi, bool ALIGN_EPI, bool SP2, class Hook>
; __device__ __forceinline__ void gemm_phase(LAS unsigned char* lds, const Gemm g, const StaticOrder& S, const Epi& E, Acc& acc, const bool fresh, const Hook& H, const int wave_id) {
;     ...
;         for (int t = t0; t < nt; t += 2) {
;             const bool last = (t == nt - 2);
;             const Src a1 = cA + (size_t)(t + 1) * kstep;
;             const Src a2 = last ? nA : cA + (size_t)(t + 2) * kstep, b2 = last ? nB : cB + (size_t)(t + 2) * kstep;
;             const Src a3 = a2 + kstep, b3 = b2 + kstep;
;             if (last && has_next) H(nxt);
;             if constexpr (SP2) {
;             PG8_TRIP_SP2(PG8_WAIT_V(8));
.LBB0_391:
	s_add_i32 s100, s56, 0xfffc0000
	v_add_u32_e32 v150, 0x10000, v148
	v_add_u32_e32 v151, 0x14000, v148
	ds_read_b128 v[132:135], v150
	ds_read_b128 v[136:139], v150 offset:1024
	ds_read_b128 v[140:143], v150 offset:2048
	ds_read_b128 v[152:155], v150 offset:3072
	ds_read_b128 v[156:159], v151
	ds_read_b128 v[160:163], v151 offset:1024
	ds_read_b128 v[164:167], v151 offset:2048
	ds_read_b128 v[168:171], v151 offset:3072
	s_mov_b32 m0, s41
	s_nop 0
	buffer_load_dwordx4 v144, s[8:11], s100 offen lds
	s_mov_b32 m0, s33
	s_nop 0
	buffer_load_dwordx4 v146, s[8:11], s100 offen lds
	s_mov_b32 m0, s45
	ds_read_b128 v[172:175], v149
	ds_read_b128 v[176:179], v149 offset:1024
	ds_read_b128 v[180:183], v149 offset:2048
	ds_read_b128 v[184:187], v149 offset:3072
	ds_read_b128 v[188:191], v149 offset:4096
	ds_read_b128 v[212:215], v149 offset:5120
	ds_read_b128 v[216:219], v149 offset:6144
	ds_read_b128 v[228:231], v149 offset:7168
	buffer_load_dwordx4 v144, s[8:11], s56 offen lds
	s_mov_b32 m0, s46
	s_nop 0
	buffer_load_dwordx4 v146, s[8:11], s56 offen lds
	s_waitcnt vmcnt(8)
	s_waitcnt lgkmcnt(0)
	s_setprio 1
	s_barrier
	v_mfma_f32_16x16x32_bf16 v[120:123], v[132:135], v[172:175], v[120:123]
	v_mfma_f32_16x16x32_bf16 v[112:115], v[140:143], v[172:175], v[112:115]
	v_mfma_f32_16x16x32_bf16 v[100:103], v[132:135], v[180:183], v[100:103]
	v_mfma_f32_16x16x32_bf16 v[88:91], v[140:143], v[180:183], v[88:91]
	v_mfma_f32_16x16x32_bf16 v[68:71], v[132:135], v[188:191], v[68:71]
	v_mfma_f32_16x16x32_bf16 v[56:59], v[140:143], v[188:191], v[56:59]
	v_mfma_f32_16x16x32_bf16 v[36:39], v[132:135], v[216:219], v[36:39]
	v_mfma_f32_16x16x32_bf16 v[28:31], v[140:143], v[216:219], v[28:31]
	v_mfma_f32_16x16x32_bf16 v[120:123], v[136:139], v[176:179], v[120:123]
	v_mfma_f32_16x16x32_bf16 v[112:115], v[152:155], v[176:179], v[112:115]
	v_mfma_f32_16x16x32_bf16 v[100:103], v[136:139], v[184:187], v[100:103]
	v_mfma_f32_16x16x32_bf16 v[88:91], v[152:155], v[184:187], v[88:91]
	v_mfma_f32_16x16x32_bf16 v[68:71], v[136:139], v[212:215], v[68:71]
	v_mfma_f32_16x16x32_bf16 v[56:59], v[152:155], v[212:215], v[56:59]
	v_mfma_f32_16x16x32_bf16 v[36:39], v[136:139], v[228:231], v[36:39]
	v_mfma_f32_16x16x32_bf16 v[28:31], v[152:155], v[228:231], v[28:31]
	v_mfma_f32_16x16x32_bf16 v[128:131], v[156:159], v[172:175], v[128:131]
	v_mfma_f32_16x16x32_bf16 v[124:127], v[164:167], v[172:175], v[124:127]
	v_mfma_f32_16x16x32_bf16 v[116:119], v[156:159], v[180:183], v[116:119]
	v_mfma_f32_16x16x32_bf16 v[108:111], v[164:167], v[180:183], v[108:111]
	v_mfma_f32_16x16x32_bf16 v[92:95], v[156:159], v[188:191], v[92:95]
	v_mfma_f32_16x16x32_bf16 v[80:83], v[164:167], v[188:191], v[80:83]
	v_mfma_f32_16x16x32_bf16 v[64:67], v[156:159], v[216:219], v[64:67]
	v_mfma_f32_16x16x32_bf16 v[48:51], v[164:167], v[216:219], v[48:51]
	v_mfma_f32_16x16x32_bf16 v[128:131], v[160:163], v[176:179], v[128:131]
	v_mfma_f32_16x16x32_bf16 v[124:127], v[168:171], v[176:179], v[124:127]
	v_mfma_f32_16x16x32_bf16 v[116:119], v[160:163], v[184:187], v[116:119]
	v_mfma_f32_16x16x32_bf16 v[108:111], v[168:171], v[184:187], v[108:111]
	v_mfma_f32_16x16x32_bf16 v[92:95], v[160:163], v[212:215], v[92:95]
	v_mfma_f32_16x16x32_bf16 v[80:83], v[168:171], v[212:215], v[80:83]
	v_mfma_f32_16x16x32_bf16 v[64:67], v[160:163], v[228:231], v[64:67]
	v_mfma_f32_16x16x32_bf16 v[48:51], v[168:171], v[228:231], v[48:51]
	s_barrier
	s_setprio 0
	s_add_i32 s12, s56, 0xfffc0080
	s_cmp_eq_u32 s29, 12
	s_cselect_b32 s60, s68, s12
	s_cselect_b32 s13, s5, s77
	s_cselect_b32 s12, s4, s76
	s_cselect_b32 s15, s7, s55
	s_cselect_b32 s14, s6, s54
	s_cselect_b32 s58, s69, s57
	s_cselect_b32 s16, s0, s8
	s_cselect_b32 s17, s1, s9
	s_cselect_b32 s18, s2, s10
	s_cselect_b32 s19, s3, s11
	s_or_b32 s59, s60, 0x80
	s_mov_b32 m0, s92
	ds_read_b128 v[172:175], v149 offset:16384
	ds_read_b128 v[176:179], v149 offset:17408
	ds_read_b128 v[180:183], v149 offset:18432
	ds_read_b128 v[184:187], v149 offset:19456
	ds_read_b128 v[188:191], v149 offset:20480
	ds_read_b128 v[212:215], v149 offset:21504
	ds_read_b128 v[216:219], v149 offset:22528
	ds_read_b128 v[228:231], v149 offset:23552
	buffer_load_dwordx4 v145, s[12:15], s58 offen lds
	s_mov_b32 m0, s93
	s_add_i32 s61, s58, 0x40000
	buffer_load_dwordx4 v147, s[12:15], s58 offen lds
	s_mov_b32 m0, s94
	s_nop 0
	buffer_load_dwordx4 v145, s[12:15], s61 offen lds
	s_mov_b32 m0, s95
	s_nop 0
	buffer_load_dwordx4 v147, s[12:15], s61 offen lds
	s_waitcnt vmcnt(6)
	s_waitcnt lgkmcnt(0)
	s_setprio 1
	s_barrier
	v_mfma_f32_16x16x32_bf16 v[72:75], v[132:135], v[172:175], v[72:75]
	v_mfma_f32_16x16x32_bf16 v[60:63], v[140:143], v[172:175], v[60:63]
	v_mfma_f32_16x16x32_bf16 v[40:43], v[132:135], v[180:183], v[40:43]
	v_mfma_f32_16x16x32_bf16 v[32:35], v[140:143], v[180:183], v[32:35]
	v_mfma_f32_16x16x32_bf16 v[16:19], v[132:135], v[188:191], v[16:19]
	v_mfma_f32_16x16x32_bf16 v[12:15], v[140:143], v[188:191], v[12:15]
	v_mfma_f32_16x16x32_bf16 v[8:11], v[132:135], v[216:219], v[8:11]
	v_mfma_f32_16x16x32_bf16 v[2:5], v[140:143], v[216:219], v[4:7]
	v_mfma_f32_16x16x32_bf16 v[72:75], v[136:139], v[176:179], v[72:75]
	v_mfma_f32_16x16x32_bf16 v[60:63], v[152:155], v[176:179], v[60:63]
	v_mfma_f32_16x16x32_bf16 v[40:43], v[136:139], v[184:187], v[40:43]
	v_mfma_f32_16x16x32_bf16 v[32:35], v[152:155], v[184:187], v[32:35]
	v_mfma_f32_16x16x32_bf16 v[16:19], v[136:139], v[212:215], v[16:19]
	v_mfma_f32_16x16x32_bf16 v[12:15], v[152:155], v[212:215], v[12:15]
	v_mfma_f32_16x16x32_bf16 v[8:11], v[136:139], v[228:231], v[8:11]
	v_mfma_f32_16x16x32_bf16 v[2:5], v[152:155], v[228:231], v[2:5]
	v_mfma_f32_16x16x32_bf16 v[96:99], v[156:159], v[172:175], v[96:99]
	v_mfma_f32_16x16x32_bf16 v[104:107], v[164:167], v[172:175], v[104:107]
	v_mfma_f32_16x16x32_bf16 v[84:87], v[156:159], v[180:183], v[84:87]
	v_mfma_f32_16x16x32_bf16 v[76:79], v[164:167], v[180:183], v[76:79]
	v_mfma_f32_16x16x32_bf16 v[52:55], v[156:159], v[188:191], v[52:55]
	v_mfma_f32_16x16x32_bf16 v[44:47], v[164:167], v[188:191], v[44:47]
	v_mfma_f32_16x16x32_bf16 v[24:27], v[156:159], v[216:219], v[24:27]
	v_mfma_f32_16x16x32_bf16 v[20:23], v[164:167], v[216:219], v[20:23]
	v_mfma_f32_16x16x32_bf16 v[96:99], v[160:163], v[176:179], v[96:99]
	v_mfma_f32_16x16x32_bf16 v[104:107], v[168:171], v[176:179], v[104:107]
	v_mfma_f32_16x16x32_bf16 v[84:87], v[160:163], v[184:187], v[84:87]
	v_mfma_f32_16x16x32_bf16 v[76:79], v[168:171], v[184:187], v[76:79]
	v_mfma_f32_16x16x32_bf16 v[52:55], v[160:163], v[212:215], v[52:55]
	v_mfma_f32_16x16x32_bf16 v[44:47], v[168:171], v[212:215], v[44:47]
	v_mfma_f32_16x16x32_bf16 v[24:27], v[160:163], v[228:231], v[24:27]
	v_mfma_f32_16x16x32_bf16 v[20:23], v[168:171], v[228:231], v[20:23]
	s_barrier
; #define PG8_BAR __builtin_amdgcn_s_barrier()
; template <class Epi, bool ALIGN_EPI, bool SP2, class Hook>
; __device__ __forceinline__ void gemm_phase(LAS unsigned char* lds, const Gemm g, const StaticOrder& S, const Epi& E, Acc& acc, const bool fresh, const Hook& H, const int wave_id) {
;     ...
;         if constexpr (ALIGN_EPI) { if (wr == 0) PG8_BAR; }
	s_setprio 0
	s_mov_b32 m0, s44
	s_nop 0
	buffer_load_dwordx4 v144, s[16:19], s60 offen lds
	s_mov_b32 m0, s36
	s_nop 0
	buffer_load_dwordx4 v146, s[16:19], s60 offen lds
	v_add_u32_e32 v152, 0x18000, v148
	v_add_u32_e32 v153, 0x1c000, v148
	ds_read_b128 v[132:135], v152
	ds_read_b128 v[136:139], v152 offset:1024
	ds_read_b128 v[140:143], v152 offset:2048
	ds_read_b128 v[154:157], v152 offset:3072
	ds_read_b128 v[158:161], v153
	ds_read_b128 v[162:165], v153 offset:1024
	ds_read_b128 v[166:169], v153 offset:2048
	ds_read_b128 v[170:173], v153 offset:3072
	s_add_i32 s60, s60, 0x40000
	s_mov_b32 m0, s37
	ds_read_b128 v[174:177], v149 offset:32768
	ds_read_b128 v[178:181], v149 offset:33792
	ds_read_b128 v[182:185], v149 offset:34816
	ds_read_b128 v[186:189], v149 offset:35840
	ds_read_b128 v[190:193], v149 offset:36864
	ds_read_b128 v[212:215], v149 offset:37888
	ds_read_b128 v[216:219], v149 offset:38912
	ds_read_b128 v[228:231], v149 offset:39936
	buffer_load_dwordx4 v144, s[16:19], s60 offen lds
	s_mov_b32 m0, s38
	s_nop 0
	buffer_load_dwordx4 v146, s[16:19], s60 offen lds
	s_waitcnt vmcnt(8)
	s_waitcnt lgkmcnt(0)
	s_setprio 1
	s_barrier
	v_mfma_f32_16x16x32_bf16 v[120:123], v[132:135], v[174:177], v[120:123]
	v_mfma_f32_16x16x32_bf16 v[112:115], v[140:143], v[174:177], v[112:115]
	v_mfma_f32_16x16x32_bf16 v[100:103], v[132:135], v[182:185], v[100:103]
	v_mfma_f32_16x16x32_bf16 v[88:91], v[140:143], v[182:185], v[88:91]
	v_mfma_f32_16x16x32_bf16 v[68:71], v[132:135], v[190:193], v[68:71]
	v_mfma_f32_16x16x32_bf16 v[56:59], v[140:143], v[190:193], v[56:59]
	v_mfma_f32_16x16x32_bf16 v[36:39], v[132:135], v[216:219], v[36:39]
	v_mfma_f32_16x16x32_bf16 v[28:31], v[140:143], v[216:219], v[28:31]
	v_mfma_f32_16x16x32_bf16 v[120:123], v[136:139], v[178:181], v[120:123]
	v_mfma_f32_16x16x32_bf16 v[112:115], v[154:157], v[178:181], v[112:115]
	v_mfma_f32_16x16x32_bf16 v[100:103], v[136:139], v[186:189], v[100:103]
	v_mfma_f32_16x16x32_bf16 v[88:91], v[154:157], v[186:189], v[88:91]
	v_mfma_f32_16x16x32_bf16 v[68:71], v[136:139], v[212:215], v[68:71]
	v_mfma_f32_16x16x32_bf16 v[56:59], v[154:157], v[212:215], v[56:59]
	v_mfma_f32_16x16x32_bf16 v[36:39], v[136:139], v[228:231], v[36:39]
	v_mfma_f32_16x16x32_bf16 v[28:31], v[154:157], v[228:231], v[28:31]
	v_mfma_f32_16x16x32_bf16 v[128:131], v[158:161], v[174:177], v[128:131]
	v_mfma_f32_16x16x32_bf16 v[124:127], v[166:169], v[174:177], v[124:127]
	v_mfma_f32_16x16x32_bf16 v[116:119], v[158:161], v[182:185], v[116:119]
	v_mfma_f32_16x16x32_bf16 v[108:111], v[166:169], v[182:185], v[108:111]
	v_mfma_f32_16x16x32_bf16 v[92:95], v[158:161], v[190:193], v[92:95]
	v_mfma_f32_16x16x32_bf16 v[80:83], v[166:169], v[190:193], v[80:83]
	v_mfma_f32_16x16x32_bf16 v[64:67], v[158:161], v[216:219], v[64:67]
	v_mfma_f32_16x16x32_bf16 v[48:51], v[166:169], v[216:219], v[48:51]
	v_mfma_f32_16x16x32_bf16 v[128:131], v[162:165], v[178:181], v[128:131]
	v_mfma_f32_16x16x32_bf16 v[124:127], v[170:173], v[178:181], v[124:127]
	v_mfma_f32_16x16x32_bf16 v[116:119], v[162:165], v[186:189], v[116:119]
	v_mfma_f32_16x16x32_bf16 v[108:111], v[170:173], v[186:189], v[108:111]
	v_mfma_f32_16x16x32_bf16 v[92:95], v[162:165], v[212:215], v[92:95]
	v_mfma_f32_16x16x32_bf16 v[80:83], v[170:173], v[212:215], v[80:83]
	v_mfma_f32_16x16x32_bf16 v[64:67], v[162:165], v[228:231], v[64:67]
	v_mfma_f32_16x16x32_bf16 v[48:51], v[170:173], v[228:231], v[48:51]
	s_barrier
	s_setprio 0
	s_mov_b32 m0, s39
	s_or_b32 s60, s58, 0x80
	ds_read_b128 v[174:177], v149 offset:49152
	ds_read_b128 v[178:181], v149 offset:50176
	ds_read_b128 v[182:185], v149 offset:51200
	ds_read_b128 v[186:189], v149 offset:52224
	ds_read_b128 v[190:193], v149 offset:53248
	ds_read_b128 v[212:215], v149 offset:54272
	ds_read_b128 v[216:219], v149 offset:55296
	ds_read_b128 v[228:231], v149 offset:56320
	buffer_load_dwordx4 v145, s[12:15], s60 offen lds
	s_mov_b32 m0, s40
	s_add_i32 s58, s58, 0x40080
	buffer_load_dwordx4 v147, s[12:15], s60 offen lds
	s_mov_b32 m0, s43
	s_nop 0
	buffer_load_dwordx4 v145, s[12:15], s58 offen lds
	s_mov_b32 m0, s42
	s_nop 0
	buffer_load_dwordx4 v147, s[12:15], s58 offen lds
	s_add_i32 s29, s29, 2
	s_addk_i32 s56, 0x100
	s_addk_i32 s57, 0x100
	s_cmp_gt_u32 s29, 13
	s_waitcnt vmcnt(6)
	s_waitcnt lgkmcnt(0)
	s_setprio 1
	s_barrier
	v_mfma_f32_16x16x32_bf16 v[72:75], v[132:135], v[174:177], v[72:75]
	v_mfma_f32_16x16x32_bf16 v[60:63], v[140:143], v[174:177], v[60:63]
	v_mfma_f32_16x16x32_bf16 v[40:43], v[132:135], v[182:185], v[40:43]
	v_mfma_f32_16x16x32_bf16 v[32:35], v[140:143], v[182:185], v[32:35]
	v_mfma_f32_16x16x32_bf16 v[16:19], v[132:135], v[190:193], v[16:19]
	v_mfma_f32_16x16x32_bf16 v[12:15], v[140:143], v[190:193], v[12:15]
	v_mfma_f32_16x16x32_bf16 v[6:9], v[132:135], v[216:219], v[8:11]
	v_mfma_f32_16x16x32_bf16 v[2:5], v[140:143], v[216:219], v[2:5]
	v_mfma_f32_16x16x32_bf16 v[72:75], v[136:139], v[178:181], v[72:75]
	v_mfma_f32_16x16x32_bf16 v[60:63], v[154:157], v[178:181], v[60:63]
	v_mfma_f32_16x16x32_bf16 v[40:43], v[136:139], v[186:189], v[40:43]
	v_mfma_f32_16x16x32_bf16 v[32:35], v[154:157], v[186:189], v[32:35]
	v_mfma_f32_16x16x32_bf16 v[16:19], v[136:139], v[212:215], v[16:19]
	v_mfma_f32_16x16x32_bf16 v[12:15], v[154:157], v[212:215], v[12:15]
	v_mfma_f32_16x16x32_bf16 v[8:11], v[136:139], v[228:231], v[6:9]
	v_mfma_f32_16x16x32_bf16 v[4:7], v[154:157], v[228:231], v[2:5]
	v_mfma_f32_16x16x32_bf16 v[96:99], v[158:161], v[174:177], v[96:99]
	v_mfma_f32_16x16x32_bf16 v[104:107], v[166:169], v[174:177], v[104:107]
	v_mfma_f32_16x16x32_bf16 v[84:87], v[158:161], v[182:185], v[84:87]
	v_mfma_f32_16x16x32_bf16 v[76:79], v[166:169], v[182:185], v[76:79]
	v_mfma_f32_16x16x32_bf16 v[52:55], v[158:161], v[190:193], v[52:55]
	v_mfma_f32_16x16x32_bf16 v[44:47], v[166:169], v[190:193], v[44:47]
	v_mfma_f32_16x16x32_bf16 v[24:27], v[158:161], v[216:219], v[24:27]
	v_mfma_f32_16x16x32_bf16 v[20:23], v[166:169], v[216:219], v[20:23]
	v_mfma_f32_16x16x32_bf16 v[96:99], v[162:165], v[178:181], v[96:99]
	v_mfma_f32_16x16x32_bf16 v[104:107], v[170:173], v[178:181], v[104:107]
	v_mfma_f32_16x16x32_bf16 v[84:87], v[162:165], v[186:189], v[84:87]
	v_mfma_f32_16x16x32_bf16 v[76:79], v[170:173], v[186:189], v[76:79]
	v_mfma_f32_16x16x32_bf16 v[52:55], v[162:165], v[212:215], v[52:55]
	v_mfma_f32_16x16x32_bf16 v[44:47], v[170:173], v[212:215], v[44:47]
	v_mfma_f32_16x16x32_bf16 v[24:27], v[162:165], v[228:231], v[24:27]
	v_mfma_f32_16x16x32_bf16 v[20:23], v[170:173], v[228:231], v[20:23]
	s_barrier
	s_setprio 0
	s_cbranch_scc0 .LBB0_391
	s_mov_b32 m0, s41
	s_nop 0
	buffer_load_dwordx4 v144, s[16:19], s59 offen lds
	s_mov_b32 m0, s33
	s_nop 0
	buffer_load_dwordx4 v146, s[16:19], s59 offen lds
	v_readlane_b32 s8, v251, 45
	v_readlane_b32 s9, v251, 46
	s_and_b64 vcc, exec, s[8:9]
	s_cbranch_vccz .LBB0_394
; #define LAS __attribute__((address_space(3)))
; #define GAS __attribute__((address_space(1)))
; __device__ __forceinline__ int opaque_tid(int wave) { unsigned z = 0u; asm volatile("" : "+v"(z)); return wave * 64 + (int)__builtin_amdgcn_mbcnt_hi(~0u, __builtin_amdgcn_mbcnt_lo(~0u, z)); }
; #define PG8_WAIT_L(n) asm volatile("s_waitcnt lgkmcnt(" #n ")" ::: "memory")
; #define PG8_BAR __builtin_amdgcn_s_barrier()
; template <class Epi, bool ALIGN_EPI, bool SP2, class Hook>
; __device__ __forceinline__ void gemm_phase(LAS unsigned char* lds, const Gemm g, const StaticOrder& S, const Epi& E, Acc& acc, const bool fresh, const Hook& H, const int wave_id) {
;     ...
;         if constexpr (ALIGN_EPI) { if (wr == 0) PG8_BAR; }
;         const int tid_ = opaque_tid(wave_id), fr_ = tid_ & 15, fq_ = (tid_ & 63) >> 4;
;         const LAS float* rstab = (const LAS float*)(lds + RSTAB_OFF);
;         if (Epi::NEEDS_RS && cur.pm != rs_pm) {
;             rs_pm = cur.pm;
;             const GAS f32x4* p = (const GAS f32x4*)(E.rowss + (size_t)(cur.pm * BM + (tid_ >> 1)) * 16) + (tid_ & 1) * 2; const f32x4 pa = p[0], pb = p[1];
;             float t = ((pa[0] + pa[1]) + (pa[2] + pa[3])) + ((pb[0] + pb[1]) + (pb[2] + pb[3]));
;             const float t2 = __shfl_xor(t, 1); t = (tid_ & 1) ? (t2 + t) : (t + t2);
;             if ((tid_ & 1) == 0) ((LAS float*)(lds + RSTAB_OFF))[tid_ >> 1] = __builtin_amdgcn_rsqf(t * (1.0f / DM) + NORM_EPS);
;             PG8_WAIT_L(0); PG8_BAR;
;         }
.LBB0_394:
	v_mov_b32_e32 v0, v1
	s_cmp_lg_u32 s65, s28
	v_mbcnt_lo_u32_b32 v0, -1, v0
	v_mbcnt_hi_u32_b32 v2, -1, v0
	s_mov_b64 s[8:9], -1
	s_cbranch_scc0 .LBB0_398
	v_readlane_b32 s8, v249, 60
	s_lshl_b32 s10, s65, 8
	v_and_b32_e32 v140, 1, v2
	v_add_u32_e32 v0, s8, v2
	v_ashrrev_i32_e32 v3, 1, v0
	v_add_u32_e32 v132, s10, v3
	v_ashrrev_i32_e32 v133, 31, v132
	v_readlane_b32 s8, v254, 51
	v_lshlrev_b64 v[132:133], 6, v[132:133]
	v_readlane_b32 s9, v254, 52
	v_lshlrev_b32_e32 v0, 5, v140
	s_nop 0
	v_lshl_add_u64 v[132:133], s[8:9], 0, v[132:133]
	v_lshl_add_u64 v[136:137], v[132:133], 0, v[0:1]
	global_load_dwordx4 v[132:135], v[136:137], off offset:16
	s_nop 0
	global_load_dwordx4 v[136:139], v[136:137], off
	s_waitcnt vmcnt(1)
	v_add_f32_e32 v132, v132, v133
	s_waitcnt vmcnt(0)
	v_add_f32_e32 v0, v136, v137
	v_add_f32_e32 v136, v138, v139
	v_add_f32_e32 v133, v134, v135
	v_add_f32_e32 v0, v0, v136
	v_add_f32_e32 v132, v132, v133
	v_and_b32_e32 v133, 64, v198
	v_add_f32_e32 v0, v0, v132
	v_xor_b32_e32 v132, 1, v198
	v_add_u32_e32 v133, 64, v133
	v_cmp_lt_i32_e32 vcc, v132, v133
	s_nop 1
	v_cndmask_b32_e32 v132, v198, v132, vcc
	v_lshlrev_b32_e32 v132, 2, v132
	ds_bpermute_b32 v132, v132, v0
	v_cmp_eq_u32_e32 vcc, 0, v140
	s_and_saveexec_b64 s[8:9], vcc
	s_cbranch_execz .LBB0_397
	s_waitcnt lgkmcnt(0)
	v_add_f32_e32 v0, v0, v132
	v_mov_b32_e32 v132, 0x358637bd
	v_fmamk_f32 v0, v0, 0x3a800000, v132
	v_rsq_f32_e32 v0, v0
	v_lshl_add_u32 v3, v3, 2, 0
	v_add_u32_e32 v3, 0x21000, v3
	ds_write_b32 v3, v0

; #define PG8_WAIT_V(n) asm volatile("s_waitcnt vmcnt(" #n ")" ::: "memory")
; #define PG8_BAR __builtin_amdgcn_s_barrier()
; template <class Epi, bool ALIGN_EPI, bool SP2, class Hook>
; __device__ __forceinline__ void gemm_phase(LAS unsigned char* lds, const Gemm g, const StaticOrder& S, const Epi& E, Acc& acc, const bool fresh, const Hook& H, const int wave_id) {
;     ...
;     PG8_WAIT_V(0);
;     if constexpr (!ALIGN_EPI) { if (wr == 0) PG8_BAR; }
;     PG8_BAR;
.LBB0_453:
	v_readlane_b32 s100, v251, 45
	v_readlane_b32 s101, v251, 46
	s_nop 0
	s_cmp_lg_u64 s[100:101], 0
	s_cbranch_scc0 .Lua_0
	s_barrier

; #define PG8_WAIT_V(n) asm volatile("s_waitcnt vmcnt(" #n ")" ::: "memory")
; template <class Epi, bool ALIGN_EPI, bool SP2, class Hook>
; __device__ __forceinline__ void gemm_phase(LAS unsigned char* lds, const Gemm g, const StaticOrder& S, const Epi& E, Acc& acc, const bool fresh, const Hook& H, const int wave_id) {
;     ...
;         for (int t = t0; t < nt; t += 2) {
;             const bool last = (t == nt - 2);
;             const Src a1 = cA + (size_t)(t + 1) * kstep;
;             const Src a2 = last ? nA : cA + (size_t)(t + 2) * kstep, b2 = last ? nB : cB + (size_t)(t + 2) * kstep;
;             const Src a3 = a2 + kstep, b3 = b2 + kstep;
;             if (last && has_next) H(nxt);
;             if constexpr (SP2) {
;             PG8_TRIP_SP2(PG8_WAIT_V(8));
.LBB0_1461:
	s_add_i32 s100, s55, 0xfffc0000
	v_add_u32_e32 v138, 0x10000, v136
	v_add_u32_e32 v139, 0x14000, v136
	ds_read_b128 v[140:143], v138
	ds_read_b128 v[144:147], v138 offset:1024
	ds_read_b128 v[148:151], v138 offset:2048
	ds_read_b128 v[152:155], v138 offset:3072
	ds_read_b128 v[156:159], v139
	ds_read_b128 v[160:163], v139 offset:1024
	ds_read_b128 v[164:167], v139 offset:2048
	ds_read_b128 v[168:171], v139 offset:3072
	s_mov_b32 m0, s41
	s_nop 0
	buffer_load_dwordx4 v132, s[12:15], s100 offen lds
	s_mov_b32 m0, s33
	s_nop 0
	buffer_load_dwordx4 v134, s[12:15], s100 offen lds
	s_mov_b32 m0, s45
	ds_read_b128 v[172:175], v137
	ds_read_b128 v[176:179], v137 offset:1024
	ds_read_b128 v[180:183], v137 offset:2048
	ds_read_b128 v[184:187], v137 offset:3072
	ds_read_b128 v[188:191], v137 offset:4096
	ds_read_b128 v[192:195], v137 offset:5120
	ds_read_b128 v[200:203], v137 offset:6144
	ds_read_b128 v[204:207], v137 offset:7168
	buffer_load_dwordx4 v132, s[12:15], s55 offen lds
	s_mov_b32 m0, s46
	s_nop 0
	buffer_load_dwordx4 v134, s[12:15], s55 offen lds
	s_waitcnt vmcnt(8)
	s_waitcnt lgkmcnt(0)
	s_setprio 1
	s_barrier
	v_mfma_f32_16x16x32_bf16 v[124:127], v[140:143], v[172:175], v[124:127]
	v_mfma_f32_16x16x32_bf16 v[116:119], v[148:151], v[172:175], v[116:119]
	v_mfma_f32_16x16x32_bf16 v[108:111], v[140:143], v[180:183], v[108:111]
	v_mfma_f32_16x16x32_bf16 v[100:103], v[148:151], v[180:183], v[100:103]
	v_mfma_f32_16x16x32_bf16 v[92:95], v[140:143], v[188:191], v[92:95]
	v_mfma_f32_16x16x32_bf16 v[84:87], v[148:151], v[188:191], v[84:87]
	v_mfma_f32_16x16x32_bf16 v[76:79], v[140:143], v[200:203], v[76:79]
	v_mfma_f32_16x16x32_bf16 v[64:67], v[148:151], v[200:203], v[64:67]
	v_mfma_f32_16x16x32_bf16 v[124:127], v[144:147], v[176:179], v[124:127]
	v_mfma_f32_16x16x32_bf16 v[116:119], v[152:155], v[176:179], v[116:119]
	v_mfma_f32_16x16x32_bf16 v[108:111], v[144:147], v[184:187], v[108:111]
	v_mfma_f32_16x16x32_bf16 v[100:103], v[152:155], v[184:187], v[100:103]
	v_mfma_f32_16x16x32_bf16 v[92:95], v[144:147], v[192:195], v[92:95]
	v_mfma_f32_16x16x32_bf16 v[84:87], v[152:155], v[192:195], v[84:87]
	v_mfma_f32_16x16x32_bf16 v[76:79], v[144:147], v[204:207], v[76:79]
	v_mfma_f32_16x16x32_bf16 v[64:67], v[152:155], v[204:207], v[64:67]
	v_mfma_f32_16x16x32_bf16 v[128:131], v[156:159], v[172:175], v[128:131]
	v_mfma_f32_16x16x32_bf16 v[120:123], v[164:167], v[172:175], v[120:123]
	v_mfma_f32_16x16x32_bf16 v[112:115], v[156:159], v[180:183], v[112:115]
	v_mfma_f32_16x16x32_bf16 v[104:107], v[164:167], v[180:183], v[104:107]
	v_mfma_f32_16x16x32_bf16 v[96:99], v[156:159], v[188:191], v[96:99]
	v_mfma_f32_16x16x32_bf16 v[88:91], v[164:167], v[188:191], v[88:91]
	v_mfma_f32_16x16x32_bf16 v[80:83], v[156:159], v[200:203], v[80:83]
	v_mfma_f32_16x16x32_bf16 v[68:71], v[164:167], v[200:203], v[68:71]
	v_mfma_f32_16x16x32_bf16 v[128:131], v[160:163], v[176:179], v[128:131]
	v_mfma_f32_16x16x32_bf16 v[120:123], v[168:171], v[176:179], v[120:123]
	v_mfma_f32_16x16x32_bf16 v[112:115], v[160:163], v[184:187], v[112:115]
	v_mfma_f32_16x16x32_bf16 v[104:107], v[168:171], v[184:187], v[104:107]
	v_mfma_f32_16x16x32_bf16 v[96:99], v[160:163], v[192:195], v[96:99]
	v_mfma_f32_16x16x32_bf16 v[88:91], v[168:171], v[192:195], v[88:91]
	v_mfma_f32_16x16x32_bf16 v[80:83], v[160:163], v[204:207], v[80:83]
	v_mfma_f32_16x16x32_bf16 v[68:71], v[168:171], v[204:207], v[68:71]
	s_barrier
	s_setprio 0
	s_add_i32 s16, s55, 0xfffc0080
	s_cmp_eq_u32 s54, 12
	s_cselect_b32 s59, s50, s16
	s_cselect_b32 s17, s9, s77
	s_cselect_b32 s16, s8, s76
	s_cselect_b32 s19, s11, s29
	s_cselect_b32 s18, s10, s28
	s_cselect_b32 s57, s51, s56
	s_cselect_b32 s20, s4, s12
	s_cselect_b32 s21, s5, s13
	s_cselect_b32 s22, s6, s14
	s_cselect_b32 s23, s7, s15
	s_or_b32 s58, s59, 0x80
	s_mov_b32 m0, s92
	ds_read_b128 v[172:175], v137 offset:16384
	ds_read_b128 v[176:179], v137 offset:17408
	ds_read_b128 v[180:183], v137 offset:18432
	ds_read_b128 v[184:187], v137 offset:19456
	ds_read_b128 v[188:191], v137 offset:20480
	ds_read_b128 v[192:195], v137 offset:21504
	ds_read_b128 v[200:203], v137 offset:22528
	ds_read_b128 v[204:207], v137 offset:23552
	buffer_load_dwordx4 v133, s[16:19], s57 offen lds
	s_mov_b32 m0, s93
	s_add_i32 s60, s57, 0x40000
	buffer_load_dwordx4 v135, s[16:19], s57 offen lds
	s_mov_b32 m0, s94
	s_nop 0
	buffer_load_dwordx4 v133, s[16:19], s60 offen lds
	s_mov_b32 m0, s95
	s_nop 0
	buffer_load_dwordx4 v135, s[16:19], s60 offen lds
	s_waitcnt vmcnt(6)
	s_waitcnt lgkmcnt(0)
	s_setprio 1
	s_barrier
; #define PG8_WAIT_V(n) asm volatile("s_waitcnt vmcnt(" #n ")" ::: "memory")
; template <class Epi, bool ALIGN_EPI, bool SP2, class Hook>
; __device__ __forceinline__ void gemm_phase(LAS unsigned char* lds, const Gemm g, const StaticOrder& S, const Epi& E, Acc& acc, const bool fresh, const Hook& H, const int wave_id) {
;     ...
;         for (int t = t0; t < nt; t += 2) {
;             const bool last = (t == nt - 2);
;             const Src a1 = cA + (size_t)(t + 1) * kstep;
;             const Src a2 = last ? nA : cA + (size_t)(t + 2) * kstep, b2 = last ? nB : cB + (size_t)(t + 2) * kstep;
;             const Src a3 = a2 + kstep, b3 = b2 + kstep;
;             if (last && has_next) H(nxt);
;             if constexpr (SP2) {
;             PG8_TRIP_SP2(PG8_WAIT_V(8));
	v_mfma_f32_16x16x32_bf16 v[60:63], v[140:143], v[172:175], v[60:63]
	v_mfma_f32_16x16x32_bf16 v[52:55], v[148:151], v[172:175], v[52:55]
	v_mfma_f32_16x16x32_bf16 v[44:47], v[140:143], v[180:183], v[44:47]
	v_mfma_f32_16x16x32_bf16 v[36:39], v[148:151], v[180:183], v[36:39]
	v_mfma_f32_16x16x32_bf16 v[28:31], v[140:143], v[188:191], v[28:31]
	v_mfma_f32_16x16x32_bf16 v[20:23], v[148:151], v[188:191], v[20:23]
	v_mfma_f32_16x16x32_bf16 v[12:15], v[140:143], v[200:203], v[12:15]
	v_mfma_f32_16x16x32_bf16 v[2:5], v[148:151], v[200:203], v[4:7]
	v_mfma_f32_16x16x32_bf16 v[60:63], v[144:147], v[176:179], v[60:63]
	v_mfma_f32_16x16x32_bf16 v[52:55], v[152:155], v[176:179], v[52:55]
	v_mfma_f32_16x16x32_bf16 v[44:47], v[144:147], v[184:187], v[44:47]
	v_mfma_f32_16x16x32_bf16 v[36:39], v[152:155], v[184:187], v[36:39]
	v_mfma_f32_16x16x32_bf16 v[28:31], v[144:147], v[192:195], v[28:31]
	v_mfma_f32_16x16x32_bf16 v[20:23], v[152:155], v[192:195], v[20:23]
	v_mfma_f32_16x16x32_bf16 v[12:15], v[144:147], v[204:207], v[12:15]
	v_mfma_f32_16x16x32_bf16 v[2:5], v[152:155], v[204:207], v[2:5]
	v_mfma_f32_16x16x32_bf16 v[72:75], v[156:159], v[172:175], v[72:75]
	v_mfma_f32_16x16x32_bf16 v[56:59], v[164:167], v[172:175], v[56:59]
	v_mfma_f32_16x16x32_bf16 v[48:51], v[156:159], v[180:183], v[48:51]
	v_mfma_f32_16x16x32_bf16 v[40:43], v[164:167], v[180:183], v[40:43]
	v_mfma_f32_16x16x32_bf16 v[32:35], v[156:159], v[188:191], v[32:35]
	v_mfma_f32_16x16x32_bf16 v[24:27], v[164:167], v[188:191], v[24:27]
	v_mfma_f32_16x16x32_bf16 v[16:19], v[156:159], v[200:203], v[16:19]
	v_mfma_f32_16x16x32_bf16 v[6:9], v[164:167], v[200:203], v[8:11]
	v_mfma_f32_16x16x32_bf16 v[72:75], v[160:163], v[176:179], v[72:75]
	v_mfma_f32_16x16x32_bf16 v[56:59], v[168:171], v[176:179], v[56:59]
	v_mfma_f32_16x16x32_bf16 v[48:51], v[160:163], v[184:187], v[48:51]
	v_mfma_f32_16x16x32_bf16 v[40:43], v[168:171], v[184:187], v[40:43]
	v_mfma_f32_16x16x32_bf16 v[32:35], v[160:163], v[192:195], v[32:35]
	v_mfma_f32_16x16x32_bf16 v[24:27], v[168:171], v[192:195], v[24:27]
	v_mfma_f32_16x16x32_bf16 v[16:19], v[160:163], v[204:207], v[16:19]
	v_mfma_f32_16x16x32_bf16 v[8:11], v[168:171], v[204:207], v[6:9]
	s_barrier
	s_setprio 0
	s_mov_b32 m0, s44
	s_nop 0
	buffer_load_dwordx4 v132, s[20:23], s59 offen lds
	s_mov_b32 m0, s36
	s_nop 0
	buffer_load_dwordx4 v134, s[20:23], s59 offen lds
	v_add_u32_e32 v140, 0x18000, v136
	v_add_u32_e32 v141, 0x1c000, v136
	ds_read_b128 v[142:145], v140
	ds_read_b128 v[146:149], v140 offset:1024
	ds_read_b128 v[150:153], v140 offset:2048
	ds_read_b128 v[154:157], v140 offset:3072
	ds_read_b128 v[158:161], v141
	ds_read_b128 v[162:165], v141 offset:1024
	ds_read_b128 v[166:169], v141 offset:2048
	ds_read_b128 v[170:173], v141 offset:3072
	s_add_i32 s59, s59, 0x40000
	s_mov_b32 m0, s37
	ds_read_b128 v[174:177], v137 offset:32768
	ds_read_b128 v[178:181], v137 offset:33792
	ds_read_b128 v[182:185], v137 offset:34816
	ds_read_b128 v[186:189], v137 offset:35840
	ds_read_b128 v[190:193], v137 offset:36864
	ds_read_b128 v[194:197], v137 offset:37888
	ds_read_b128 v[200:203], v137 offset:38912
	ds_read_b128 v[204:207], v137 offset:39936
	buffer_load_dwordx4 v132, s[20:23], s59 offen lds
	s_mov_b32 m0, s38
	s_nop 0
	buffer_load_dwordx4 v134, s[20:23], s59 offen lds
	s_waitcnt vmcnt(8)
	s_waitcnt lgkmcnt(0)
	s_setprio 1
	s_barrier
	v_mfma_f32_16x16x32_bf16 v[124:127], v[142:145], v[174:177], v[124:127]
	v_mfma_f32_16x16x32_bf16 v[116:119], v[150:153], v[174:177], v[116:119]
	v_mfma_f32_16x16x32_bf16 v[108:111], v[142:145], v[182:185], v[108:111]
	v_mfma_f32_16x16x32_bf16 v[100:103], v[150:153], v[182:185], v[100:103]
	v_mfma_f32_16x16x32_bf16 v[92:95], v[142:145], v[190:193], v[92:95]
	v_mfma_f32_16x16x32_bf16 v[84:87], v[150:153], v[190:193], v[84:87]
	v_mfma_f32_16x16x32_bf16 v[76:79], v[142:145], v[200:203], v[76:79]
	v_mfma_f32_16x16x32_bf16 v[64:67], v[150:153], v[200:203], v[64:67]
	v_mfma_f32_16x16x32_bf16 v[124:127], v[146:149], v[178:181], v[124:127]
	v_mfma_f32_16x16x32_bf16 v[116:119], v[154:157], v[178:181], v[116:119]
	v_mfma_f32_16x16x32_bf16 v[108:111], v[146:149], v[186:189], v[108:111]
	v_mfma_f32_16x16x32_bf16 v[100:103], v[154:157], v[186:189], v[100:103]
	v_mfma_f32_16x16x32_bf16 v[92:95], v[146:149], v[194:197], v[92:95]
	v_mfma_f32_16x16x32_bf16 v[84:87], v[154:157], v[194:197], v[84:87]
	v_mfma_f32_16x16x32_bf16 v[76:79], v[146:149], v[204:207], v[76:79]
	v_mfma_f32_16x16x32_bf16 v[64:67], v[154:157], v[204:207], v[64:67]
	v_mfma_f32_16x16x32_bf16 v[128:131], v[158:161], v[174:177], v[128:131]
	v_mfma_f32_16x16x32_bf16 v[120:123], v[166:169], v[174:177], v[120:123]
	v_mfma_f32_16x16x32_bf16 v[112:115], v[158:161], v[182:185], v[112:115]
	v_mfma_f32_16x16x32_bf16 v[104:107], v[166:169], v[182:185], v[104:107]
	v_mfma_f32_16x16x32_bf16 v[96:99], v[158:161], v[190:193], v[96:99]
	v_mfma_f32_16x16x32_bf16 v[88:91], v[166:169], v[190:193], v[88:91]
	v_mfma_f32_16x16x32_bf16 v[80:83], v[158:161], v[200:203], v[80:83]
	v_mfma_f32_16x16x32_bf16 v[68:71], v[166:169], v[200:203], v[68:71]
	v_mfma_f32_16x16x32_bf16 v[128:131], v[162:165], v[178:181], v[128:131]
	v_mfma_f32_16x16x32_bf16 v[120:123], v[170:173], v[178:181], v[120:123]
	v_mfma_f32_16x16x32_bf16 v[112:115], v[162:165], v[186:189], v[112:115]
	v_mfma_f32_16x16x32_bf16 v[104:107], v[170:173], v[186:189], v[104:107]
	v_mfma_f32_16x16x32_bf16 v[96:99], v[162:165], v[194:197], v[96:99]
	v_mfma_f32_16x16x32_bf16 v[88:91], v[170:173], v[194:197], v[88:91]
	v_mfma_f32_16x16x32_bf16 v[80:83], v[162:165], v[204:207], v[80:83]
	v_mfma_f32_16x16x32_bf16 v[68:71], v[170:173], v[204:207], v[68:71]
	s_barrier
; #define LAS __attribute__((address_space(3)))
; #define GAS __attribute__((address_space(1)))
; __device__ __forceinline__ int opaque_tid(int wave) { unsigned z = 0u; asm volatile("" : "+v"(z)); return wave * 64 + (int)__builtin_amdgcn_mbcnt_hi(~0u, __builtin_amdgcn_mbcnt_lo(~0u, z)); }
; #define PG8_BAR __builtin_amdgcn_s_barrier()
; template <class Epi, bool ALIGN_EPI, bool SP2, class Hook>
; __device__ __forceinline__ void gemm_phase(LAS unsigned char* lds, const Gemm g, const StaticOrder& S, const Epi& E, Acc& acc, const bool fresh, const Hook& H, const int wave_id) {
;     ...
;         if constexpr (ALIGN_EPI) { if (wr == 0) PG8_BAR; }
;         const int tid_ = opaque_tid(wave_id), fr_ = tid_ & 15, fq_ = (tid_ & 63) >> 4;
;         const LAS float* rstab = (const LAS float*)(lds + RSTAB_OFF);
;         if (Epi::NEEDS_RS && cur.pm != rs_pm) {
;             rs_pm = cur.pm;
;             const GAS f32x4* p = (const GAS f32x4*)(E.rowss + (size_t)(cur.pm * BM + (tid_ >> 1)) * 16) + (tid_ & 1) * 2; const f32x4 pa = p[0], pb = p[1];
;             float t = ((pa[0] + pa[1]) + (pa[2] + pa[3])) + ((pb[0] + pb[1]) + (pb[2] + pb[3]));
;             const float t2 = __shfl_xor(t, 1); t = (tid_ & 1) ? (t2 + t) : (t + t2);
;             if ((tid_ & 1) == 0) ((LAS float*)(lds + RSTAB_OFF))[tid_ >> 1] = __builtin_amdgcn_rsqf(t * (1.0f / DM) + NORM_EPS);
	s_setprio 0
	s_mov_b32 m0, s39
	s_or_b32 s59, s57, 0x80
	ds_read_b128 v[174:177], v137 offset:49152
	ds_read_b128 v[178:181], v137 offset:50176
	ds_read_b128 v[182:185], v137 offset:51200
	ds_read_b128 v[186:189], v137 offset:52224
	ds_read_b128 v[190:193], v137 offset:53248
	ds_read_b128 v[194:197], v137 offset:54272
	ds_read_b128 v[200:203], v137 offset:55296
	ds_read_b128 v[204:207], v137 offset:56320
	buffer_load_dwordx4 v133, s[16:19], s59 offen lds
	s_mov_b32 m0, s40
	s_add_i32 s57, s57, 0x40080
	buffer_load_dwordx4 v135, s[16:19], s59 offen lds
	s_mov_b32 m0, s43
	s_nop 0
	buffer_load_dwordx4 v133, s[16:19], s57 offen lds
	s_mov_b32 m0, s42
	s_nop 0
	buffer_load_dwordx4 v135, s[16:19], s57 offen lds
	s_add_i32 s54, s54, 2
	s_addk_i32 s55, 0x100
	s_addk_i32 s56, 0x100
	s_cmp_gt_u32 s54, 13
	s_waitcnt vmcnt(6)
	s_waitcnt lgkmcnt(0)
	s_setprio 1
	s_barrier
	v_mfma_f32_16x16x32_bf16 v[60:63], v[142:145], v[174:177], v[60:63]
	v_mfma_f32_16x16x32_bf16 v[52:55], v[150:153], v[174:177], v[52:55]
	v_mfma_f32_16x16x32_bf16 v[44:47], v[142:145], v[182:185], v[44:47]
	v_mfma_f32_16x16x32_bf16 v[36:39], v[150:153], v[182:185], v[36:39]
	v_mfma_f32_16x16x32_bf16 v[28:31], v[142:145], v[190:193], v[28:31]
	v_mfma_f32_16x16x32_bf16 v[20:23], v[150:153], v[190:193], v[20:23]
	v_mfma_f32_16x16x32_bf16 v[12:15], v[142:145], v[200:203], v[12:15]
	v_mfma_f32_16x16x32_bf16 v[2:5], v[150:153], v[200:203], v[2:5]
	v_mfma_f32_16x16x32_bf16 v[60:63], v[146:149], v[178:181], v[60:63]
	v_mfma_f32_16x16x32_bf16 v[52:55], v[154:157], v[178:181], v[52:55]
	v_mfma_f32_16x16x32_bf16 v[44:47], v[146:149], v[186:189], v[44:47]
	v_mfma_f32_16x16x32_bf16 v[36:39], v[154:157], v[186:189], v[36:39]
	v_mfma_f32_16x16x32_bf16 v[28:31], v[146:149], v[194:197], v[28:31]
	v_mfma_f32_16x16x32_bf16 v[20:23], v[154:157], v[194:197], v[20:23]
	v_mfma_f32_16x16x32_bf16 v[12:15], v[146:149], v[204:207], v[12:15]
	v_mfma_f32_16x16x32_bf16 v[4:7], v[154:157], v[204:207], v[2:5]
	v_mfma_f32_16x16x32_bf16 v[72:75], v[158:161], v[174:177], v[72:75]
	v_mfma_f32_16x16x32_bf16 v[56:59], v[166:169], v[174:177], v[56:59]
	v_mfma_f32_16x16x32_bf16 v[48:51], v[158:161], v[182:185], v[48:51]
	v_mfma_f32_16x16x32_bf16 v[40:43], v[166:169], v[182:185], v[40:43]
	v_mfma_f32_16x16x32_bf16 v[32:35], v[158:161], v[190:193], v[32:35]
	v_mfma_f32_16x16x32_bf16 v[24:27], v[166:169], v[190:193], v[24:27]
	v_mfma_f32_16x16x32_bf16 v[16:19], v[158:161], v[200:203], v[16:19]
	v_mfma_f32_16x16x32_bf16 v[8:11], v[166:169], v[200:203], v[8:11]
	v_mfma_f32_16x16x32_bf16 v[72:75], v[162:165], v[178:181], v[72:75]
	v_mfma_f32_16x16x32_bf16 v[56:59], v[170:173], v[178:181], v[56:59]
	v_mfma_f32_16x16x32_bf16 v[48:51], v[162:165], v[186:189], v[48:51]
	v_mfma_f32_16x16x32_bf16 v[40:43], v[170:173], v[186:189], v[40:43]
	v_mfma_f32_16x16x32_bf16 v[32:35], v[162:165], v[194:197], v[32:35]
	v_mfma_f32_16x16x32_bf16 v[24:27], v[170:173], v[194:197], v[24:27]
	v_mfma_f32_16x16x32_bf16 v[16:19], v[162:165], v[204:207], v[16:19]
	v_mfma_f32_16x16x32_bf16 v[8:11], v[170:173], v[204:207], v[8:11]
	s_barrier
	s_setprio 0
	s_cbranch_scc0 .LBB0_1461
	s_mov_b32 m0, s41
	s_nop 0
	buffer_load_dwordx4 v132, s[20:23], s58 offen lds
	s_mov_b32 m0, s33
	s_nop 0
	buffer_load_dwordx4 v134, s[20:23], s58 offen lds
	v_readlane_b32 s12, v251, 45
	v_readlane_b32 s13, v251, 46
	s_and_b64 vcc, exec, s[12:13]
	s_cbranch_vccz .LBB0_1464
.LBB0_1464:
	v_mov_b32_e32 v0, v1
	s_cmp_lg_u32 s31, s53
	v_mbcnt_lo_u32_b32 v0, -1, v0
	v_mbcnt_hi_u32_b32 v2, -1, v0
	s_mov_b64 s[12:13], -1
	s_mov_b32 s15, s73
	s_cbranch_scc0 .LBB0_1468
	v_readlane_b32 s12, v249, 60
	s_lshl_b32 s14, s31, 8
	v_and_b32_e32 v150, 1, v2
	v_add_u32_e32 v0, s12, v2
	v_ashrrev_i32_e32 v3, 1, v0
	v_add_u32_e32 v142, s14, v3
	v_ashrrev_i32_e32 v143, 31, v142
	v_lshlrev_b64 v[142:143], 6, v[142:143]
	v_lshl_add_u64 v[142:143], s[26:27], 0, v[142:143]
	v_lshlrev_b32_e32 v0, 5, v150
	v_lshl_add_u64 v[146:147], v[142:143], 0, v[0:1]
	global_load_dwordx4 v[142:145], v[146:147], off offset:16
	s_nop 0
	global_load_dwordx4 v[146:149], v[146:147], off
	s_waitcnt vmcnt(1)
	v_add_f32_e32 v142, v142, v143
	s_waitcnt vmcnt(0)
	v_add_f32_e32 v0, v146, v147
	v_add_f32_e32 v146, v148, v149
	v_add_f32_e32 v143, v144, v145
	v_add_f32_e32 v0, v0, v146
	v_add_f32_e32 v142, v142, v143
	v_and_b32_e32 v143, 64, v198
	v_add_f32_e32 v0, v0, v142
	v_xor_b32_e32 v142, 1, v198
	v_add_u32_e32 v143, 64, v143
	v_cmp_lt_i32_e32 vcc, v142, v143
	s_nop 1
	v_cndmask_b32_e32 v142, v198, v142, vcc
	v_lshlrev_b32_e32 v142, 2, v142
	ds_bpermute_b32 v142, v142, v0
	v_cmp_eq_u32_e32 vcc, 0, v150
	s_and_saveexec_b64 s[12:13], vcc
	s_cbranch_execz .LBB0_1467
	s_waitcnt lgkmcnt(0)
	v_add_f32_e32 v0, v0, v142
	v_mov_b32_e32 v142, 0x358637bd
	v_fmamk_f32 v0, v0, 0x3a800000, v142
	v_rsq_f32_e32 v0, v0
	v_lshl_add_u32 v3, v3, 2, 0
	v_add_u32_e32 v3, 0x21000, v3
	ds_write_b32 v3, v0

; #define LAS __attribute__((address_space(3)))
; __device__ __forceinline__ u32x4 pack8(const float (&v)[8]) { u32x4 w; w.x = pk2(v[0], v[1]); w.y = pk2(v[2], v[3]); w.z = pk2(v[4], v[5]); w.w = pk2(v[6], v[7]); return w; }
;     __device__ __forceinline__ bool operator()(Acc& acc, const Unit& u, int wr, int wc, int fr, int fq, const LAS float* rstab) const {
;         bf16_t* p0 = H + (size_t)(u.pm * BM + wr * 64 + fr) * HD_PITCH + u.pn * HALF + wc * 32 + 8 * fq;
;         const LAS float* rsp = rstab + wr * 64 + fr;
; #pragma unroll
;         for (int ai = 0; ai < 2; ++ai)
; #pragma unroll
;             for (int m = 0; m < 4; ++m) {
;                 const float rs = rsp[ai * HALF + m * 16], nrs = -LOG2E * rs, rs2 = rs * rs;
;                 float v[8];
; #pragma unroll
;                 for (int n = 0; n < 2; ++n)
; #pragma unroll
;                     for (int e = 0; e < 4; ++e) {
;                         const float g = acc[ai][0][m][n][e], up = acc[ai][1][m][n][e];
;                         v[4 * n + e] = (g * up * rs2) * __builtin_amdgcn_rcpf(1.0f + __builtin_amdgcn_exp2f(g * nrs));
;                     }
;                 gst<u32x4>(p0 + (ai * HALF + m * 16) * HD_PITCH, pack8(v));
;                 asm volatile("" ::: "memory");
;             }
.LBB0_1470:
	v_readlane_b32 s12, v250, 1
	v_and_b32_e32 v0, 15, v2
	s_add_i32 s12, s14, s12
	v_or_b32_e32 v3, s12, v0
	v_readlane_b32 s12, v254, 57
	v_readlane_b32 s13, v254, 58
	v_pk_mul_f32 v[130:131], v[126:127], v[130:131]
	v_pk_mul_f32 v[122:123], v[118:119], v[122:123]
	s_waitcnt lgkmcnt(0)
	v_mov_b64_e32 v[142:143], s[12:13]
	s_movk_i32 s12, 0x1800
	v_mad_i64_i32 v[142:143], s[12:13], v3, s12, v[142:143]
	s_lshl_b32 s12, s52, 7
	s_ashr_i32 s13, s12, 31
	v_lshl_add_u64 v[144:145], s[12:13], 1, v[142:143]
	v_readlane_b32 s12, v250, 11
	v_pk_mul_f32 v[114:115], v[110:111], v[114:115]
	v_pk_mul_f32 v[106:107], v[102:103], v[106:107]
	v_lshl_add_u32 v142, v0, 2, s12
	ds_read_b32 v143, v142
	v_readlane_b32 s12, v254, 33
	s_mov_b32 s14, s12
	v_lshl_add_u64 v[144:145], v[144:145], 0, s[14:15]
	v_and_b32_e32 v0, 48, v2
	s_waitcnt lgkmcnt(0)
	v_mul_f32_e32 v146, 0xbfb8aa3b, v143
	v_pk_mul_f32 v[126:127], v[126:127], v[146:147] op_sel_hi:[1,0]
	v_exp_f32_e32 v126, v126
	v_exp_f32_e32 v127, v127
	v_lshl_add_u64 v[2:3], v[144:145], 0, v[0:1]
	v_mul_f32_e32 v0, v124, v146
	v_exp_f32_e32 v144, v0
	v_mul_f32_e32 v0, v125, v146
	v_exp_f32_e32 v145, v0
	v_mul_f32_e32 v0, v143, v143
	v_pk_mul_f32 v[124:125], v[124:125], v[128:129]
	v_pk_add_f32 v[126:127], v[126:127], 1.0 op_sel_hi:[1,0]
	v_pk_mul_f32 v[128:129], v[130:131], v[0:1] op_sel_hi:[1,0]
	v_pk_mul_f32 v[130:131], v[116:117], v[146:147] op_sel_hi:[1,0]
	v_rcp_f32_e32 v126, v126
	v_rcp_f32_e32 v127, v127
	v_exp_f32_e32 v130, v130
	v_exp_f32_e32 v131, v131
	v_pk_mul_f32 v[118:119], v[118:119], v[146:147] op_sel_hi:[1,0]
	v_exp_f32_e32 v118, v118
	v_exp_f32_e32 v119, v119
	v_add_f32_e32 v143, 1.0, v144
	v_pk_mul_f32 v[126:127], v[128:129], v[126:127]
	v_pk_add_f32 v[128:129], v[130:131], 1.0 op_sel_hi:[1,0]
	v_rcp_f32_e32 v144, v143
	v_add_f32_e32 v143, 1.0, v145
	v_rcp_f32_e32 v128, v128
	v_rcp_f32_e32 v129, v129
	v_pk_add_f32 v[118:119], v[118:119], 1.0 op_sel_hi:[1,0]
	v_rcp_f32_e32 v145, v143
	v_rcp_f32_e32 v118, v118
	v_rcp_f32_e32 v119, v119
	v_pk_mul_f32 v[116:117], v[116:117], v[120:121]
	v_pk_mul_f32 v[124:125], v[124:125], v[0:1] op_sel_hi:[1,0]
	v_pk_mul_f32 v[116:117], v[116:117], v[0:1] op_sel_hi:[1,0]
	v_pk_mul_f32 v[124:125], v[124:125], v[144:145]
	v_pk_mul_f32 v[120:121], v[116:117], v[128:129]
	v_pk_mul_f32 v[116:117], v[122:123], v[0:1] op_sel_hi:[1,0]
	v_readlane_b32 s13, v254, 34
	v_pk_mul_f32 v[122:123], v[116:117], v[118:119]
	v_cvt_pk_bf16_f32 v116, v124, v125
	v_cvt_pk_bf16_f32 v117, v126, v127
	v_cvt_pk_bf16_f32 v118, v120, v121
	v_cvt_pk_bf16_f32 v119, v122, v123
	global_store_dwordx4 v[2:3], v[116:119], off
	ds_read_b32 v0, v142 offset:64
	v_writelane_b32 v254, s12, 33
	v_pk_mul_f32 v[98:99], v[94:95], v[98:99]
	v_pk_mul_f32 v[90:91], v[86:87], v[90:91]
	v_writelane_b32 v254, s13, 34
	s_waitcnt lgkmcnt(0)
	v_mul_f32_e32 v118, 0xbfb8aa3b, v0
	v_pk_mul_f32 v[110:111], v[110:111], v[118:119] op_sel_hi:[1,0]
	v_exp_f32_e32 v110, v110
	v_exp_f32_e32 v111, v111
	v_mul_f32_e32 v0, v0, v0
	v_pk_mul_f32 v[116:117], v[108:109], v[118:119] op_sel_hi:[1,0]
	v_pk_mul_f32 v[108:109], v[108:109], v[112:113]
	v_pk_add_f32 v[110:111], v[110:111], 1.0 op_sel_hi:[1,0]
	v_pk_mul_f32 v[112:113], v[114:115], v[0:1] op_sel_hi:[1,0]
	v_pk_mul_f32 v[114:115], v[100:101], v[118:119] op_sel_hi:[1,0]
	v_rcp_f32_e32 v110, v110
	v_rcp_f32_e32 v111, v111
	v_exp_f32_e32 v114, v114
	v_exp_f32_e32 v115, v115
	v_pk_mul_f32 v[102:103], v[102:103], v[118:119] op_sel_hi:[1,0]
	v_exp_f32_e32 v116, v116
	v_exp_f32_e32 v117, v117
	v_exp_f32_e32 v102, v102
	v_exp_f32_e32 v103, v103
	v_pk_mul_f32 v[110:111], v[112:113], v[110:111]
	v_pk_add_f32 v[112:113], v[114:115], 1.0 op_sel_hi:[1,0]
	v_pk_add_f32 v[116:117], v[116:117], 1.0 op_sel_hi:[1,0]
	v_rcp_f32_e32 v112, v112
	v_rcp_f32_e32 v113, v113
	v_pk_add_f32 v[102:103], v[102:103], 1.0 op_sel_hi:[1,0]
	v_rcp_f32_e32 v116, v116
	v_rcp_f32_e32 v117, v117
	v_rcp_f32_e32 v102, v102
	v_rcp_f32_e32 v103, v103
	v_pk_mul_f32 v[100:101], v[100:101], v[104:105]
	v_pk_mul_f32 v[108:109], v[108:109], v[0:1] op_sel_hi:[1,0]
	v_pk_mul_f32 v[100:101], v[100:101], v[0:1] op_sel_hi:[1,0]
	s_mov_b32 s12, 0x18000
	v_pk_mul_f32 v[104:105], v[100:101], v[112:113]
	v_pk_mul_f32 v[100:101], v[106:107], v[0:1] op_sel_hi:[1,0]
	v_pk_mul_f32 v[108:109], v[108:109], v[116:117]
	v_pk_mul_f32 v[106:107], v[100:101], v[102:103]
	v_cvt_pk_bf16_f32 v102, v104, v105
	v_add_co_u32_e32 v104, vcc, s12, v2
	v_cvt_pk_bf16_f32 v100, v108, v109
	v_cvt_pk_bf16_f32 v101, v110, v111
	v_cvt_pk_bf16_f32 v103, v106, v107
	v_addc_co_u32_e32 v105, vcc, 0, v3, vcc
	global_store_dwordx4 v[104:105], v[100:103], off
	ds_read_b32 v0, v142 offset:128
	s_mov_b32 s12, 0x30000
	v_pk_mul_f32 v[82:83], v[78:79], v[82:83]
	v_pk_mul_f32 v[70:71], v[66:67], v[70:71]
	v_pk_mul_f32 v[58:59], v[54:55], v[58:59]
	s_waitcnt lgkmcnt(0)
; #define LAS __attribute__((address_space(3)))
; __device__ __forceinline__ u32x4 pack8(const float (&v)[8]) { u32x4 w; w.x = pk2(v[0], v[1]); w.y = pk2(v[2], v[3]); w.z = pk2(v[4], v[5]); w.w = pk2(v[6], v[7]); return w; }
;     __device__ __forceinline__ bool operator()(Acc& acc, const Unit& u, int wr, int wc, int fr, int fq, const LAS float* rstab) const {
;         bf16_t* p0 = H + (size_t)(u.pm * BM + wr * 64 + fr) * HD_PITCH + u.pn * HALF + wc * 32 + 8 * fq;
;         const LAS float* rsp = rstab + wr * 64 + fr;
; #pragma unroll
;         for (int ai = 0; ai < 2; ++ai)
; #pragma unroll
;             for (int m = 0; m < 4; ++m) {
;                 const float rs = rsp[ai * HALF + m * 16], nrs = -LOG2E * rs, rs2 = rs * rs;
;                 float v[8];
; #pragma unroll
;                 for (int n = 0; n < 2; ++n)
; #pragma unroll
;                     for (int e = 0; e < 4; ++e) {
;                         const float g = acc[ai][0][m][n][e], up = acc[ai][1][m][n][e];
;                         v[4 * n + e] = (g * up * rs2) * __builtin_amdgcn_rcpf(1.0f + __builtin_amdgcn_exp2f(g * nrs));
;                     }
;                 gst<u32x4>(p0 + (ai * HALF + m * 16) * HD_PITCH, pack8(v));
;                 asm volatile("" ::: "memory");
;             }
	v_mul_f32_e32 v102, 0xbfb8aa3b, v0
	v_pk_mul_f32 v[94:95], v[94:95], v[102:103] op_sel_hi:[1,0]
	v_exp_f32_e32 v94, v94
	v_exp_f32_e32 v95, v95
	v_mul_f32_e32 v0, v0, v0
	v_pk_mul_f32 v[100:101], v[92:93], v[102:103] op_sel_hi:[1,0]
	v_pk_mul_f32 v[92:93], v[92:93], v[96:97]
	v_pk_add_f32 v[94:95], v[94:95], 1.0 op_sel_hi:[1,0]
	v_pk_mul_f32 v[96:97], v[98:99], v[0:1] op_sel_hi:[1,0]
	v_pk_mul_f32 v[98:99], v[84:85], v[102:103] op_sel_hi:[1,0]
	v_rcp_f32_e32 v94, v94
	v_rcp_f32_e32 v95, v95
	v_exp_f32_e32 v98, v98
	v_exp_f32_e32 v99, v99
	v_pk_mul_f32 v[86:87], v[86:87], v[102:103] op_sel_hi:[1,0]
	v_exp_f32_e32 v100, v100
	v_exp_f32_e32 v101, v101
	v_exp_f32_e32 v86, v86
	v_exp_f32_e32 v87, v87
	v_pk_mul_f32 v[94:95], v[96:97], v[94:95]
	v_pk_add_f32 v[96:97], v[98:99], 1.0 op_sel_hi:[1,0]
	v_pk_add_f32 v[100:101], v[100:101], 1.0 op_sel_hi:[1,0]
	v_rcp_f32_e32 v96, v96
	v_rcp_f32_e32 v97, v97
	v_pk_add_f32 v[86:87], v[86:87], 1.0 op_sel_hi:[1,0]
	v_rcp_f32_e32 v100, v100
	v_rcp_f32_e32 v101, v101
	v_rcp_f32_e32 v86, v86
	v_rcp_f32_e32 v87, v87
	v_pk_mul_f32 v[84:85], v[84:85], v[88:89]
	v_pk_mul_f32 v[92:93], v[92:93], v[0:1] op_sel_hi:[1,0]
	v_pk_mul_f32 v[84:85], v[84:85], v[0:1] op_sel_hi:[1,0]
	v_pk_mul_f32 v[92:93], v[92:93], v[100:101]
	v_pk_mul_f32 v[88:89], v[84:85], v[96:97]
	v_pk_mul_f32 v[84:85], v[90:91], v[0:1] op_sel_hi:[1,0]
	v_pk_mul_f32 v[50:51], v[46:47], v[50:51]
	v_pk_mul_f32 v[90:91], v[84:85], v[86:87]
	v_cvt_pk_bf16_f32 v86, v88, v89
	v_add_co_u32_e32 v88, vcc, s12, v2
	v_cvt_pk_bf16_f32 v84, v92, v93
	v_cvt_pk_bf16_f32 v85, v94, v95
	v_cvt_pk_bf16_f32 v87, v90, v91
	v_addc_co_u32_e32 v89, vcc, 0, v3, vcc
	global_store_dwordx4 v[88:89], v[84:87], off
	ds_read_b32 v0, v142 offset:192
	s_mov_b32 s12, 0x48000
	v_pk_mul_f32 v[42:43], v[38:39], v[42:43]
	v_pk_mul_f32 v[34:35], v[30:31], v[34:35]
	v_pk_mul_f32 v[26:27], v[22:23], v[26:27]
	s_waitcnt lgkmcnt(0)
	v_mul_f32_e32 v86, 0xbfb8aa3b, v0
	v_pk_mul_f32 v[78:79], v[78:79], v[86:87] op_sel_hi:[1,0]
	v_exp_f32_e32 v78, v78
	v_exp_f32_e32 v79, v79
	v_mul_f32_e32 v0, v0, v0
	v_pk_mul_f32 v[84:85], v[76:77], v[86:87] op_sel_hi:[1,0]
	v_pk_mul_f32 v[76:77], v[76:77], v[80:81]
	v_pk_add_f32 v[78:79], v[78:79], 1.0 op_sel_hi:[1,0]
	v_pk_mul_f32 v[80:81], v[82:83], v[0:1] op_sel_hi:[1,0]
	v_pk_mul_f32 v[82:83], v[64:65], v[86:87] op_sel_hi:[1,0]
	v_rcp_f32_e32 v78, v78
	v_rcp_f32_e32 v79, v79
	v_exp_f32_e32 v82, v82
	v_exp_f32_e32 v83, v83
	v_pk_mul_f32 v[66:67], v[66:67], v[86:87] op_sel_hi:[1,0]
	v_exp_f32_e32 v84, v84
	v_exp_f32_e32 v85, v85
	v_exp_f32_e32 v66, v66
	v_exp_f32_e32 v67, v67
	v_pk_mul_f32 v[78:79], v[80:81], v[78:79]
	v_pk_add_f32 v[80:81], v[82:83], 1.0 op_sel_hi:[1,0]
	v_pk_add_f32 v[84:85], v[84:85], 1.0 op_sel_hi:[1,0]
	v_rcp_f32_e32 v80, v80
	v_rcp_f32_e32 v81, v81
	v_pk_add_f32 v[66:67], v[66:67], 1.0 op_sel_hi:[1,0]
	v_rcp_f32_e32 v84, v84
	v_rcp_f32_e32 v85, v85
	v_rcp_f32_e32 v66, v66
	v_rcp_f32_e32 v67, v67
	v_pk_mul_f32 v[64:65], v[64:65], v[68:69]
	v_pk_mul_f32 v[76:77], v[76:77], v[0:1] op_sel_hi:[1,0]
	v_pk_mul_f32 v[64:65], v[64:65], v[0:1] op_sel_hi:[1,0]
	v_pk_mul_f32 v[76:77], v[76:77], v[84:85]
	v_pk_mul_f32 v[68:69], v[64:65], v[80:81]
	v_pk_mul_f32 v[64:65], v[70:71], v[0:1] op_sel_hi:[1,0]
	v_pk_mul_f32 v[18:19], v[14:15], v[18:19]
	v_pk_mul_f32 v[70:71], v[64:65], v[66:67]
	v_cvt_pk_bf16_f32 v66, v68, v69
	v_add_co_u32_e32 v68, vcc, s12, v2
	v_cvt_pk_bf16_f32 v64, v76, v77
	v_cvt_pk_bf16_f32 v65, v78, v79
	v_cvt_pk_bf16_f32 v67, v70, v71
	v_addc_co_u32_e32 v69, vcc, 0, v3, vcc
	global_store_dwordx4 v[68:69], v[64:67], off
	ds_read_b32 v0, v142 offset:512
	s_mov_b32 s12, 0xc0000
	v_pk_mul_f32 v[66:67], v[62:63], v[74:75]
	v_pk_mul_f32 v[10:11], v[6:7], v[10:11]
	s_waitcnt lgkmcnt(0)
	v_mul_f32_e32 v68, 0xbfb8aa3b, v0
	v_pk_mul_f32 v[64:65], v[60:61], v[68:69] op_sel_hi:[1,0]
	v_exp_f32_e32 v64, v64
	v_exp_f32_e32 v65, v65
	v_pk_mul_f32 v[62:63], v[62:63], v[68:69] op_sel_hi:[1,0]
	v_pk_add_f32 v[64:65], v[64:65], 1.0 op_sel_hi:[1,0]
	v_rcp_f32_e32 v64, v64
	v_rcp_f32_e32 v65, v65
	v_exp_f32_e32 v62, v62
	v_exp_f32_e32 v63, v63
	v_mul_f32_e32 v0, v0, v0
	v_pk_mul_f32 v[60:61], v[60:61], v[72:73]
	v_add_f32_e32 v62, 1.0, v62
	v_pk_mul_f32 v[60:61], v[60:61], v[0:1] op_sel_hi:[1,0]
	v_add_f32_e32 v63, 1.0, v63
	v_pk_mul_f32 v[60:61], v[60:61], v[64:65]
	v_pk_mul_f32 v[64:65], v[66:67], v[0:1] op_sel_hi:[1,0]
	v_pk_mul_f32 v[66:67], v[52:53], v[68:69] op_sel_hi:[1,0]
	v_rcp_f32_e32 v62, v62
	v_rcp_f32_e32 v63, v63
	v_exp_f32_e32 v66, v66
	v_exp_f32_e32 v67, v67
	v_pk_mul_f32 v[54:55], v[54:55], v[68:69] op_sel_hi:[1,0]
	v_exp_f32_e32 v54, v54
	v_exp_f32_e32 v55, v55
	v_pk_mul_f32 v[62:63], v[64:65], v[62:63]
	v_pk_add_f32 v[64:65], v[66:67], 1.0 op_sel_hi:[1,0]
	v_rcp_f32_e32 v64, v64
	v_rcp_f32_e32 v65, v65
	v_pk_add_f32 v[54:55], v[54:55], 1.0 op_sel_hi:[1,0]
	v_rcp_f32_e32 v54, v54
	v_rcp_f32_e32 v55, v55
	v_pk_mul_f32 v[52:53], v[52:53], v[56:57]
	s_nop 0
	v_pk_mul_f32 v[52:53], v[52:53], v[0:1] op_sel_hi:[1,0]
	s_nop 0
	v_pk_mul_f32 v[56:57], v[52:53], v[64:65]
	v_pk_mul_f32 v[52:53], v[58:59], v[0:1] op_sel_hi:[1,0]
	s_nop 0
	v_pk_mul_f32 v[58:59], v[52:53], v[54:55]
	v_cvt_pk_bf16_f32 v54, v56, v57
	v_add_co_u32_e32 v56, vcc, s12, v2
	v_cvt_pk_bf16_f32 v52, v60, v61
	v_cvt_pk_bf16_f32 v53, v62, v63
	v_cvt_pk_bf16_f32 v55, v58, v59
	v_addc_co_u32_e32 v57, vcc, 0, v3, vcc
	global_store_dwordx4 v[56:57], v[52:55], off
	ds_read_b32 v0, v142 offset:576
	s_mov_b32 s12, 0xd8000
	s_waitcnt lgkmcnt(0)
; __device__ __forceinline__ u32x4 pack8(const float (&v)[8]) { u32x4 w; w.x = pk2(v[0], v[1]); w.y = pk2(v[2], v[3]); w.z = pk2(v[4], v[5]); w.w = pk2(v[6], v[7]); return w; }
; #define PG8_BAR __builtin_amdgcn_s_barrier()
;     __device__ __forceinline__ bool operator()(Acc& acc, const Unit& u, int wr, int wc, int fr, int fq, const LAS float* rstab) const {
;     ...
; #pragma unroll
;         for (int ai = 0; ai < 2; ++ai)
; #pragma unroll
;             for (int m = 0; m < 4; ++m) {
;                 const float rs = rsp[ai * HALF + m * 16], nrs = -LOG2E * rs, rs2 = rs * rs;
;                 float v[8];
; #pragma unroll
;                 for (int n = 0; n < 2; ++n)
; #pragma unroll
;                     for (int e = 0; e < 4; ++e) {
;                         const float g = acc[ai][0][m][n][e], up = acc[ai][1][m][n][e];
;                         v[4 * n + e] = (g * up * rs2) * __builtin_amdgcn_rcpf(1.0f + __builtin_amdgcn_exp2f(g * nrs));
;                     }
;                 gst<u32x4>(p0 + (ai * HALF + m * 16) * HD_PITCH, pack8(v));
;                 asm volatile("" ::: "memory");
;             }
; template <class Epi, bool ALIGN_EPI, bool SP2, class Hook>
; __device__ __forceinline__ void gemm_phase(LAS unsigned char* lds, const Gemm g, const StaticOrder& S, const Epi& E, Acc& acc, const bool fresh, const Hook& H, const int wave_id) {
;     ...
;         if (!has_next) break;
;         if (reset) {
; #pragma unroll
;             for (int a = 0; a < 2; ++a)
; #pragma unroll
;                 for (int b = 0; b < 2; ++b)
; #pragma unroll
;                     for (int m = 0; m < 4; ++m)
; #pragma unroll
;                         for (int n = 0; n < 2; ++n) acc[a][b][m][n] = (f32x4){0.f, 0.f, 0.f, 0.f};
;         }
;         cur = nxt; cA = nA; cB = nB; ++ui;
;         if constexpr (ALIGN_EPI) { if (wr == 1) PG8_BAR; }
	v_mul_f32_e32 v54, 0xbfb8aa3b, v0
	v_pk_mul_f32 v[46:47], v[46:47], v[54:55] op_sel_hi:[1,0]
	v_exp_f32_e32 v46, v46
	v_exp_f32_e32 v47, v47
	v_mul_f32_e32 v0, v0, v0
	v_pk_mul_f32 v[52:53], v[44:45], v[54:55] op_sel_hi:[1,0]
	v_pk_mul_f32 v[44:45], v[44:45], v[48:49]
	v_pk_add_f32 v[46:47], v[46:47], 1.0 op_sel_hi:[1,0]
	v_pk_mul_f32 v[48:49], v[50:51], v[0:1] op_sel_hi:[1,0]
	v_pk_mul_f32 v[50:51], v[36:37], v[54:55] op_sel_hi:[1,0]
	v_rcp_f32_e32 v46, v46
	v_rcp_f32_e32 v47, v47
	v_exp_f32_e32 v50, v50
	v_exp_f32_e32 v51, v51
	v_pk_mul_f32 v[38:39], v[38:39], v[54:55] op_sel_hi:[1,0]
	v_exp_f32_e32 v52, v52
	v_exp_f32_e32 v53, v53
	v_exp_f32_e32 v38, v38
	v_exp_f32_e32 v39, v39
	v_pk_mul_f32 v[46:47], v[48:49], v[46:47]
	v_pk_add_f32 v[48:49], v[50:51], 1.0 op_sel_hi:[1,0]
	v_pk_add_f32 v[52:53], v[52:53], 1.0 op_sel_hi:[1,0]
	v_rcp_f32_e32 v48, v48
	v_rcp_f32_e32 v49, v49
	v_pk_add_f32 v[38:39], v[38:39], 1.0 op_sel_hi:[1,0]
	v_rcp_f32_e32 v52, v52
	v_rcp_f32_e32 v53, v53
	v_rcp_f32_e32 v38, v38
	v_rcp_f32_e32 v39, v39
	v_pk_mul_f32 v[36:37], v[36:37], v[40:41]
	v_pk_mul_f32 v[44:45], v[44:45], v[0:1] op_sel_hi:[1,0]
	v_pk_mul_f32 v[36:37], v[36:37], v[0:1] op_sel_hi:[1,0]
	v_pk_mul_f32 v[44:45], v[44:45], v[52:53]
	v_pk_mul_f32 v[40:41], v[36:37], v[48:49]
	v_pk_mul_f32 v[36:37], v[42:43], v[0:1] op_sel_hi:[1,0]
	s_nop 0
	v_pk_mul_f32 v[42:43], v[36:37], v[38:39]
	v_cvt_pk_bf16_f32 v38, v40, v41
	v_add_co_u32_e32 v40, vcc, s12, v2
	v_cvt_pk_bf16_f32 v36, v44, v45
	v_cvt_pk_bf16_f32 v37, v46, v47
	v_cvt_pk_bf16_f32 v39, v42, v43
	v_addc_co_u32_e32 v41, vcc, 0, v3, vcc
	global_store_dwordx4 v[40:41], v[36:39], off
	ds_read_b32 v0, v142 offset:640
	s_mov_b32 s12, 0xf0000
	s_waitcnt lgkmcnt(0)
	v_mul_f32_e32 v38, 0xbfb8aa3b, v0
	v_pk_mul_f32 v[30:31], v[30:31], v[38:39] op_sel_hi:[1,0]
	v_exp_f32_e32 v30, v30
	v_exp_f32_e32 v31, v31
	v_mul_f32_e32 v0, v0, v0
	v_pk_mul_f32 v[36:37], v[28:29], v[38:39] op_sel_hi:[1,0]
	v_pk_mul_f32 v[28:29], v[28:29], v[32:33]
	v_pk_add_f32 v[30:31], v[30:31], 1.0 op_sel_hi:[1,0]
	v_pk_mul_f32 v[32:33], v[34:35], v[0:1] op_sel_hi:[1,0]
	v_pk_mul_f32 v[34:35], v[20:21], v[38:39] op_sel_hi:[1,0]
	v_rcp_f32_e32 v30, v30
	v_rcp_f32_e32 v31, v31
	v_exp_f32_e32 v34, v34
	v_exp_f32_e32 v35, v35
	v_pk_mul_f32 v[22:23], v[22:23], v[38:39] op_sel_hi:[1,0]
	v_exp_f32_e32 v36, v36
	v_exp_f32_e32 v37, v37
	v_exp_f32_e32 v22, v22
	v_exp_f32_e32 v23, v23
	v_pk_mul_f32 v[30:31], v[32:33], v[30:31]
	v_pk_add_f32 v[32:33], v[34:35], 1.0 op_sel_hi:[1,0]
	v_pk_add_f32 v[36:37], v[36:37], 1.0 op_sel_hi:[1,0]
	v_rcp_f32_e32 v32, v32
	v_rcp_f32_e32 v33, v33
	v_pk_add_f32 v[22:23], v[22:23], 1.0 op_sel_hi:[1,0]
	v_rcp_f32_e32 v36, v36
	v_rcp_f32_e32 v37, v37
	v_rcp_f32_e32 v22, v22
	v_rcp_f32_e32 v23, v23
	v_pk_mul_f32 v[20:21], v[20:21], v[24:25]
	v_pk_mul_f32 v[28:29], v[28:29], v[0:1] op_sel_hi:[1,0]
	v_pk_mul_f32 v[20:21], v[20:21], v[0:1] op_sel_hi:[1,0]
	v_pk_mul_f32 v[28:29], v[28:29], v[36:37]
	v_pk_mul_f32 v[24:25], v[20:21], v[32:33]
	v_pk_mul_f32 v[20:21], v[26:27], v[0:1] op_sel_hi:[1,0]
	s_nop 0
	v_pk_mul_f32 v[26:27], v[20:21], v[22:23]
	v_cvt_pk_bf16_f32 v22, v24, v25
	v_add_co_u32_e32 v24, vcc, s12, v2
	v_cvt_pk_bf16_f32 v20, v28, v29
	v_cvt_pk_bf16_f32 v21, v30, v31
	v_cvt_pk_bf16_f32 v23, v26, v27
	v_addc_co_u32_e32 v25, vcc, 0, v3, vcc
	global_store_dwordx4 v[24:25], v[20:23], off
	ds_read_b32 v0, v142 offset:704
	v_add_co_u32_e32 v2, vcc, 0x108000, v2
	s_waitcnt lgkmcnt(0)
	v_mul_f32_e32 v22, 0xbfb8aa3b, v0
	v_pk_mul_f32 v[14:15], v[14:15], v[22:23] op_sel_hi:[1,0]
	v_exp_f32_e32 v14, v14
	v_exp_f32_e32 v15, v15
	v_mul_f32_e32 v0, v0, v0
	v_pk_mul_f32 v[20:21], v[12:13], v[22:23] op_sel_hi:[1,0]
	v_pk_mul_f32 v[12:13], v[12:13], v[16:17]
	v_pk_add_f32 v[14:15], v[14:15], 1.0 op_sel_hi:[1,0]
	v_pk_mul_f32 v[16:17], v[18:19], v[0:1] op_sel_hi:[1,0]
	v_pk_mul_f32 v[18:19], v[4:5], v[22:23] op_sel_hi:[1,0]
	v_rcp_f32_e32 v14, v14
	v_rcp_f32_e32 v15, v15
	v_exp_f32_e32 v18, v18
	v_exp_f32_e32 v19, v19
	v_pk_mul_f32 v[6:7], v[6:7], v[22:23] op_sel_hi:[1,0]
	v_exp_f32_e32 v20, v20
	v_exp_f32_e32 v21, v21
	v_exp_f32_e32 v6, v6
	v_exp_f32_e32 v7, v7
	v_pk_mul_f32 v[14:15], v[16:17], v[14:15]
	v_pk_add_f32 v[16:17], v[18:19], 1.0 op_sel_hi:[1,0]
	v_pk_add_f32 v[20:21], v[20:21], 1.0 op_sel_hi:[1,0]
	v_rcp_f32_e32 v16, v16
	v_rcp_f32_e32 v17, v17
	v_pk_add_f32 v[6:7], v[6:7], 1.0 op_sel_hi:[1,0]
	v_rcp_f32_e32 v20, v20
	v_rcp_f32_e32 v21, v21
	v_rcp_f32_e32 v6, v6
	v_rcp_f32_e32 v7, v7
	v_pk_mul_f32 v[4:5], v[4:5], v[8:9]
	v_pk_mul_f32 v[12:13], v[12:13], v[0:1] op_sel_hi:[1,0]
	v_pk_mul_f32 v[4:5], v[4:5], v[0:1] op_sel_hi:[1,0]
	v_pk_mul_f32 v[12:13], v[12:13], v[20:21]
	v_pk_mul_f32 v[8:9], v[4:5], v[16:17]
	v_pk_mul_f32 v[4:5], v[10:11], v[0:1] op_sel_hi:[1,0]
	v_addc_co_u32_e32 v3, vcc, 0, v3, vcc
	v_pk_mul_f32 v[10:11], v[4:5], v[6:7]
	v_cvt_pk_bf16_f32 v4, v12, v13
	v_cvt_pk_bf16_f32 v5, v14, v15
	v_cvt_pk_bf16_f32 v6, v8, v9
	v_cvt_pk_bf16_f32 v7, v10, v11
	global_store_dwordx4 v[2:3], v[4:7], off
	s_and_b64 vcc, exec, s[2:3]
	s_mov_b64 s[2:3], -1
	s_cbranch_vccnz .LBB0_1453
	v_mov_b32_e32 v225, v198
	v_mov_b64_e32 v[198:199], 0x5bf
	v_mov_b32_e32 v0, 1
	v_mov_b64_e32 v[226:227], 0x5c0
	v_mov_b64_e32 v[246:247], 0xff
	v_mov_b64_e32 v[244:245], 0x100
	s_and_b64 vcc, exec, s[0:1]
	s_cbranch_vccnz .LBB0_1452
	s_branch .LBB0_1452
